# scan phases: parameter / operand load chains (prompt A, prompt C, sample scan) issued together instead of one waited pair at a time
# baseline (speedup 1.0000x reference)
; __device__ __forceinline__ unsigned cvt_pk_bf16(float lo, float hi) { unsigned r; asm volatile("v_cvt_pk_bf16_f32 %0, %1, %2" : "=v"(r) : "v"(lo), "v"(hi)); return r; }
; template <bool PROJECT> ...
;     ...
;     if (reload) {
;       lre = lamp[0]; lim = lamp[1];
;       const float* bbg = bbp - (size_t)lane * 32;
; #pragma unroll
;       for (int i = 0; i < 4; ++i) { const float* bp = bbg + (size_t)(16 * i + (lane & 15)) * 32 + c0;
; #pragma unroll
;           for (int pr = 0; pr < 2; ++pr) { const f32x4 a0 = *(const f32x4*)(bp + 16 * pr), a1 = *(const f32x4*)(bp + 16 * pr + 4);
;               u32x4 w; w.x = cvt_pk_bf16(a0[0], a0[1]); w.y = cvt_pk_bf16(a0[2], a0[3]); w.z = cvt_pk_bf16(a1[0], a1[1]); w.w = cvt_pk_bf16(a1[2], a1[3]);
;               bop[pr][i] = __builtin_bit_cast(bf16x8, w); } }
;       dv = PROJECT ? dsk[g * 16 + c] : 0.f;
.LBB0_1458:
	s_mov_b32 s6, s4
	s_and_b32 s4, s26, 63
	s_cmp_eq_u32 s4, s6
	s_cbranch_scc1 .LBB0_1460
	v_lshl_or_b32 v8, s4, 6, v192
	v_lshlrev_b32_e32 v0, 7, v8
	v_mov_b32_e32 v1, v48
	v_lshl_add_u64 v[32:33], v[172:173], 0, v[0:1]
	global_load_dwordx4 v[36:39], v[32:33], off
	global_load_dwordx4 v[40:43], v[32:33], off offset:16
	v_lshlrev_b32_e32 v8, 4, v8
	global_load_dwordx2 v[52:53], v8, s[36:37]
	s_movk_i32 s6, 0x1000
	v_add_co_u32_e32 v34, vcc, s6, v32
	s_mov_b64 s[6:7], 0x1000
	s_nop 0
	v_addc_co_u32_e32 v35, vcc, 0, v33, vcc
	v_lshl_add_u64 v[20:21], v[32:33], 0, s[6:7]
	s_mov_b64 s[6:7], 0x1040
	v_lshl_add_u64 v[24:25], v[32:33], 0, s[6:7]
	s_mov_b64 s[6:7], 0x1800
	v_lshl_add_u64 v[28:29], v[32:33], 0, s[6:7]
	s_mov_b64 s[6:7], 0x1840
	global_load_dwordx4 v[44:47], v[32:33], off offset:64
	global_load_dwordx4 v[54:57], v[32:33], off offset:80
	global_load_dwordx4 v[58:61], v[32:33], off offset:2048
	global_load_dwordx4 v[62:65], v[32:33], off offset:2064
	global_load_dwordx4 v[66:69], v[32:33], off offset:2112
	global_load_dwordx4 v[76:79], v[32:33], off offset:2128
	v_lshl_add_u64 v[32:33], v[32:33], 0, s[6:7]
	global_load_dwordx4 v[80:83], v[34:35], off
	global_load_dwordx4 v[84:87], v[20:21], off offset:16
	global_load_dwordx4 v[88:91], v[34:35], off offset:64
	global_load_dwordx4 v[92:95], v[24:25], off offset:16
	global_load_dwordx4 v[96:99], v[34:35], off offset:2048
	global_load_dwordx4 v[100:103], v[28:29], off offset:16
	global_load_dwordx4 v[104:107], v[34:35], off offset:2112
	global_load_dwordx4 v[108:111], v[32:33], off offset:16
	s_waitcnt vmcnt(0)
	v_cvt_pk_bf16_f32 v0, v36, v37
	v_cvt_pk_bf16_f32 v1, v38, v39
	v_cvt_pk_bf16_f32 v2, v40, v41
	v_cvt_pk_bf16_f32 v3, v42, v43
	v_cvt_pk_bf16_f32 v4, v44, v45
	v_cvt_pk_bf16_f32 v5, v46, v47
	v_cvt_pk_bf16_f32 v6, v54, v55
	v_cvt_pk_bf16_f32 v7, v56, v57
	v_cvt_pk_bf16_f32 v8, v58, v59
	v_cvt_pk_bf16_f32 v9, v60, v61
	v_cvt_pk_bf16_f32 v10, v62, v63
	v_cvt_pk_bf16_f32 v11, v64, v65
	v_cvt_pk_bf16_f32 v12, v66, v67
	v_cvt_pk_bf16_f32 v13, v68, v69
	v_cvt_pk_bf16_f32 v14, v76, v77
	v_cvt_pk_bf16_f32 v15, v78, v79
	v_cvt_pk_bf16_f32 v16, v80, v81
	v_cvt_pk_bf16_f32 v17, v82, v83
	v_cvt_pk_bf16_f32 v18, v84, v85
	v_cvt_pk_bf16_f32 v19, v86, v87
	v_cvt_pk_bf16_f32 v20, v88, v89
	v_cvt_pk_bf16_f32 v21, v90, v91
	v_cvt_pk_bf16_f32 v22, v92, v93
	v_cvt_pk_bf16_f32 v23, v94, v95
	v_cvt_pk_bf16_f32 v24, v96, v97
	v_cvt_pk_bf16_f32 v25, v98, v99
	v_cvt_pk_bf16_f32 v26, v100, v101
	v_cvt_pk_bf16_f32 v27, v102, v103
	v_cvt_pk_bf16_f32 v28, v104, v105
	v_cvt_pk_bf16_f32 v29, v106, v107
	v_cvt_pk_bf16_f32 v30, v108, v109
	v_cvt_pk_bf16_f32 v31, v110, v111

; __device__ __forceinline__ unsigned cvt_pk_bf16(float lo, float hi) { unsigned r; asm volatile("v_cvt_pk_bf16_f32 %0, %1, %2" : "=v"(r) : "v"(lo), "v"(hi)); return r; }
; template <bool PROJECT> ...
;     ...
;     if (reload) {
;       lre = lamp[0]; lim = lamp[1];
;       const float* bbg = bbp - (size_t)lane * 32;
; #pragma unroll
;       for (int i = 0; i < 4; ++i) { const float* bp = bbg + (size_t)(16 * i + (lane & 15)) * 32 + c0;
; #pragma unroll
;           for (int pr = 0; pr < 2; ++pr) { const f32x4 a0 = *(const f32x4*)(bp + 16 * pr), a1 = *(const f32x4*)(bp + 16 * pr + 4);
;               u32x4 w; w.x = cvt_pk_bf16(a0[0], a0[1]); w.y = cvt_pk_bf16(a0[2], a0[3]); w.z = cvt_pk_bf16(a1[0], a1[1]); w.w = cvt_pk_bf16(a1[2], a1[3]);
;               bop[pr][i] = __builtin_bit_cast(bf16x8, w); } }
;       dv = PROJECT ? dsk[g * 16 + c] : 0.f;
;     }
;     if (PROJECT && reload) {
; #pragma unroll
;         for (int ks = 0; ks < 4; ++ks) { const size_t co = (size_t)(g * 16 + c) * 64 + 16 * ks + 4 * tq;
;             const f32x4 a0 = *(const f32x4*)(c_re + co), a1 = *(const f32x4*)(c_im + co);
;             u32x4 w; w.x = cvt_pk_bf16(a0[0], -a1[0]); w.y = cvt_pk_bf16(a0[1], -a1[1]); w.z = cvt_pk_bf16(a0[2], -a1[2]); w.w = cvt_pk_bf16(a0[3], -a1[3]);
;             cop[ks] = __builtin_bit_cast(bf16x8, w); }
;     }
;     const int utt = lane >> 2, ucc = (lane & 3) * 4;
;     f32x4 uh[4];
; #pragma unroll
;     for (int i = 0; i < 4; ++i) { uh[i] = (f32x4){0.f, 0.f, 0.f, 0.f}; if (16 * i + utt < ntok) uh[i] = *(const f32x4*)(ubuf + (size_t)(row0 + 16 * i + utt) * D + g * 16 + ucc); }
.LBB0_1470:
	s_ashr_i32 s40, s4, 2
	s_and_b32 s6, s5, 24
	s_add_i32 s52, s6, s67
	s_ashr_i32 s41, s40, 31
	s_lshl_b64 s[6:7], s[52:53], 12
	s_lshl_b64 s[30:31], s[40:41], 6
	s_add_u32 s6, s6, s30
	s_addc_u32 s7, s7, s31
	v_mov_b32_e32 v55, s7
	v_or_b32_e32 v54, s6, v192
	s_load_dwordx2 s[6:7], s[0:1], 0x28
	v_lshl_or_b32 v2, s40, 6, v192
	s_lshl_b32 s40, s40, 4
	s_lshl_b32 s26, s52, 3
	s_addk_i32 s26, 0x4000
	s_waitcnt lgkmcnt(0)
	v_lshl_add_u64 v[0:1], v[54:55], 3, s[6:7]
	global_load_dwordx2 v[56:57], v[0:1], off
	v_lshlrev_b32_e32 v0, 2, v2
	v_lshlrev_b32_e32 v2, 5, v2
	v_ashrrev_i32_e32 v1, 31, v0
	v_ashrrev_i32_e32 v3, 31, v2
	v_lshl_add_u64 v[0:1], v[0:1], 2, s[36:37]
	v_lshl_add_u64 v[16:17], v[2:3], 2, v[172:173]
	global_load_dwordx2 v[58:59], v[0:1], off
	global_load_dwordx4 v[76:79], v[16:17], off offset:16
	global_load_dwordx4 v[96:99], v[16:17], off
	s_mov_b64 s[6:7], 0x1000
	s_ashr_i32 s41, s40, 31
	global_load_dwordx4 v[100:103], v[16:17], off offset:80
	global_load_dwordx4 v[104:107], v[16:17], off offset:64
	global_load_dwordx4 v[108:111], v[16:17], off offset:2064
	global_load_dwordx4 v[180:183], v[16:17], off offset:2048
	global_load_dwordx4 v[184:187], v[16:17], off offset:2128
	global_load_dwordx4 v[206:209], v[16:17], off offset:2112
	v_lshl_add_u64 v[18:19], v[16:17], 0, s[6:7]
	s_movk_i32 s6, 0x1000
	v_add_co_u32_e32 v40, vcc, s6, v16
	s_mov_b64 s[6:7], 0x1040
	s_nop 0
	v_addc_co_u32_e32 v41, vcc, 0, v17, vcc
	global_load_dwordx4 v[210:213], v[40:41], off
	global_load_dwordx4 v[214:217], v[18:19], off offset:16
	v_lshl_add_u64 v[18:19], v[16:17], 0, s[6:7]
	s_mov_b64 s[6:7], 0x1800
	global_load_dwordx4 v[218:221], v[40:41], off offset:64
	global_load_dwordx4 v[222:225], v[18:19], off offset:16
	v_lshl_add_u64 v[18:19], v[16:17], 0, s[6:7]
	s_mov_b64 s[6:7], 0x1840
	global_load_dwordx4 v[226:229], v[40:41], off offset:2048
	global_load_dwordx4 v[230:233], v[18:19], off offset:16
	v_lshl_add_u64 v[24:25], v[16:17], 0, s[6:7]
	global_load_dwordx4 v[234:237], v[40:41], off offset:2112
	global_load_dwordx4 v[238:241], v[24:25], off offset:16
	v_or_b32_e32 v16, s40, v161
	v_ashrrev_i32_e32 v17, 31, v16
	v_lshlrev_b64 v[24:25], 8, v[16:17]
	v_lshl_or_b32 v24, v150, 2, v24
	v_lshl_add_u64 v[50:51], s[50:51], 0, v[24:25]
	v_lshl_add_u64 v[48:49], s[48:49], 0, v[24:25]
	s_waitcnt vmcnt(0)
	v_cvt_pk_bf16_f32 v0, v96, v97
	v_cvt_pk_bf16_f32 v1, v98, v99
	v_cvt_pk_bf16_f32 v2, v76, v77
	v_cvt_pk_bf16_f32 v3, v78, v79
	v_cvt_pk_bf16_f32 v4, v104, v105
	v_cvt_pk_bf16_f32 v5, v106, v107
	v_cvt_pk_bf16_f32 v6, v100, v101
	v_cvt_pk_bf16_f32 v7, v102, v103
	v_cvt_pk_bf16_f32 v8, v180, v181
	v_cvt_pk_bf16_f32 v9, v182, v183
	v_cvt_pk_bf16_f32 v10, v108, v109
	v_cvt_pk_bf16_f32 v11, v110, v111
	v_cvt_pk_bf16_f32 v12, v206, v207
	v_cvt_pk_bf16_f32 v13, v208, v209
	v_cvt_pk_bf16_f32 v14, v184, v185
	v_cvt_pk_bf16_f32 v15, v186, v187
	v_cvt_pk_bf16_f32 v20, v210, v211
	v_cvt_pk_bf16_f32 v21, v212, v213
	v_cvt_pk_bf16_f32 v22, v214, v215
	v_cvt_pk_bf16_f32 v23, v216, v217
	v_cvt_pk_bf16_f32 v28, v218, v219
	v_cvt_pk_bf16_f32 v29, v220, v221
	v_cvt_pk_bf16_f32 v30, v222, v223
	v_cvt_pk_bf16_f32 v31, v224, v225
	v_cvt_pk_bf16_f32 v36, v226, v227
	v_cvt_pk_bf16_f32 v37, v228, v229
	v_cvt_pk_bf16_f32 v38, v230, v231
	v_cvt_pk_bf16_f32 v39, v232, v233
	v_cvt_pk_bf16_f32 v44, v234, v235
	v_cvt_pk_bf16_f32 v45, v236, v237
	v_cvt_pk_bf16_f32 v46, v238, v239
	v_cvt_pk_bf16_f32 v47, v240, v241
	global_load_dwordx4 v[76:79], v[50:51], off
	s_load_dwordx2 s[6:7], s[0:1], 0xa8
	s_waitcnt lgkmcnt(0)
	v_lshl_add_u64 v[18:19], v[16:17], 2, s[6:7]
	global_load_dword v67, v[18:19], off
	global_load_dwordx4 v[96:99], v[48:49], off
	global_load_dwordx4 v[100:103], v[48:49], off offset:64
	global_load_dwordx4 v[104:107], v[50:51], off offset:64
	global_load_dwordx4 v[108:111], v[48:49], off offset:128
	global_load_dwordx4 v[180:183], v[50:51], off offset:128
	global_load_dwordx4 v[184:187], v[48:49], off offset:192
	global_load_dwordx4 v[206:209], v[50:51], off offset:192
	s_waitcnt vmcnt(0)
	v_xor_b32_e32 v24, 0x80000000, v76
	v_cvt_pk_bf16_f32 v16, v96, v24
	v_xor_b32_e32 v24, 0x80000000, v77
	v_cvt_pk_bf16_f32 v17, v97, v24
	v_xor_b32_e32 v24, 0x80000000, v78
	v_cvt_pk_bf16_f32 v18, v98, v24
	v_xor_b32_e32 v24, 0x80000000, v79
	v_cvt_pk_bf16_f32 v19, v99, v24
	v_xor_b32_e32 v32, 0x80000000, v104
	v_cvt_pk_bf16_f32 v24, v100, v32
	v_xor_b32_e32 v32, 0x80000000, v105
	v_cvt_pk_bf16_f32 v25, v101, v32
	v_xor_b32_e32 v32, 0x80000000, v106
	v_cvt_pk_bf16_f32 v26, v102, v32
	v_xor_b32_e32 v32, 0x80000000, v107
	v_cvt_pk_bf16_f32 v27, v103, v32
	v_xor_b32_e32 v40, 0x80000000, v180
	v_cvt_pk_bf16_f32 v32, v108, v40
	v_xor_b32_e32 v40, 0x80000000, v181
	v_cvt_pk_bf16_f32 v33, v109, v40
	v_xor_b32_e32 v40, 0x80000000, v182
	v_cvt_pk_bf16_f32 v34, v110, v40
	v_xor_b32_e32 v40, 0x80000000, v183
	v_cvt_pk_bf16_f32 v35, v111, v40
	v_xor_b32_e32 v48, 0x80000000, v206
	v_cvt_pk_bf16_f32 v40, v184, v48
	v_xor_b32_e32 v48, 0x80000000, v207
	v_cvt_pk_bf16_f32 v41, v185, v48
	v_xor_b32_e32 v48, 0x80000000, v208
	v_cvt_pk_bf16_f32 v42, v186, v48
	v_xor_b32_e32 v48, 0x80000000, v209
	v_cvt_pk_bf16_f32 v43, v187, v48
	v_mov_b32_e32 v48, 0
	v_mov_b32_e32 v49, 0
	v_mov_b32_e32 v50, 0
	v_mov_b32_e32 v51, 0
	s_and_saveexec_b64 s[54:55], s[46:47]
	s_cbranch_execz .LBB0_1472
	v_or_b32_e32 v52, s26, v165
	v_lshl_add_u64 v[48:49], s[40:41], 2, v[176:177]
	v_lshlrev_b64 v[50:51], 12, v[52:53]
	v_lshl_add_u64 v[48:49], v[48:49], 0, v[50:51]
	global_load_dwordx4 v[48:51], v[48:49], off

; __device__ __forceinline__ unsigned cvt_pk_bf16(float lo, float hi) { unsigned r; asm volatile("v_cvt_pk_bf16_f32 %0, %1, %2" : "=v"(r) : "v"(lo), "v"(hi)); return r; }
; template <bool PROJECT> ...
;     ...
;     if (reload) {
;       lre = lamp[0]; lim = lamp[1];
;       const float* bbg = bbp - (size_t)lane * 32;
; #pragma unroll
;       for (int i = 0; i < 4; ++i) { const float* bp = bbg + (size_t)(16 * i + (lane & 15)) * 32 + c0;
; #pragma unroll
;           for (int pr = 0; pr < 2; ++pr) { const f32x4 a0 = *(const f32x4*)(bp + 16 * pr), a1 = *(const f32x4*)(bp + 16 * pr + 4);
;               u32x4 w; w.x = cvt_pk_bf16(a0[0], a0[1]); w.y = cvt_pk_bf16(a0[2], a0[3]); w.z = cvt_pk_bf16(a1[0], a1[1]); w.w = cvt_pk_bf16(a1[2], a1[3]);
;               bop[pr][i] = __builtin_bit_cast(bf16x8, w); } }
;       dv = PROJECT ? dsk[g * 16 + c] : 0.f;
;     }
;     if (PROJECT && reload) {
; #pragma unroll
;         for (int ks = 0; ks < 4; ++ks) { const size_t co = (size_t)(g * 16 + c) * 64 + 16 * ks + 4 * tq;
;             const f32x4 a0 = *(const f32x4*)(c_re + co), a1 = *(const f32x4*)(c_im + co);
;             u32x4 w; w.x = cvt_pk_bf16(a0[0], -a1[0]); w.y = cvt_pk_bf16(a0[1], -a1[1]); w.z = cvt_pk_bf16(a0[2], -a1[2]); w.w = cvt_pk_bf16(a0[3], -a1[3]);
;             cop[ks] = __builtin_bit_cast(bf16x8, w); }
;     }
.LBB0_1535:
	s_mov_b32 s40, s44
	s_lshl_b32 s45, s43, 6
	s_mov_b64 s[48:49], -1
	s_and_b64 vcc, exec, s[28:29]
	s_cbranch_vccz .LBB0_1537
	v_or_b32_e32 v58, s45, v192
	v_lshlrev_b32_e32 v180, 7, v58
	v_lshl_add_u64 v[56:57], v[172:173], 0, v[180:181]
	global_load_dwordx4 v[60:63], v[56:57], off
	global_load_dwordx4 v[64:67], v[56:57], off offset:16
	v_lshlrev_b32_e32 v58, 4, v58
	global_load_dwordx2 v[190:191], v58, s[36:37]
	s_movk_i32 s6, 0x1000
	v_add_co_u32_e32 v58, vcc, s6, v56
	s_mov_b64 s[6:7], 0x1000
	s_nop 0
	v_addc_co_u32_e32 v59, vcc, 0, v57, vcc
	s_lshl_b32 s28, s43, 4
	s_mov_b64 s[48:49], 0
	v_mov_b32_e32 v180, s28
	global_load_dwordx4 v[68:71], v[56:57], off offset:64
	global_load_dwordx4 v[72:75], v[56:57], off offset:80
	global_load_dwordx4 v[76:79], v[56:57], off offset:2048
	global_load_dwordx4 v[80:83], v[56:57], off offset:2064
	global_load_dwordx4 v[84:87], v[56:57], off offset:2112
	global_load_dwordx4 v[88:91], v[56:57], off offset:2128
	v_lshl_add_u64 v[52:53], v[56:57], 0, s[6:7]
	global_load_dwordx4 v[92:95], v[58:59], off
	s_mov_b64 s[6:7], 0x1040
	global_load_dwordx4 v[96:99], v[52:53], off offset:16
	v_lshl_add_u64 v[52:53], v[56:57], 0, s[6:7]
	global_load_dwordx4 v[100:103], v[58:59], off offset:64
	s_mov_b64 s[6:7], 0x1800
	global_load_dwordx4 v[104:107], v[52:53], off offset:16
	v_lshl_add_u64 v[52:53], v[56:57], 0, s[6:7]
	global_load_dwordx4 v[108:111], v[58:59], off offset:2048
	s_mov_b64 s[6:7], 0x1840
	global_load_dwordx4 v[140:143], v[52:53], off offset:16
	v_lshl_add_u64 v[52:53], v[56:57], 0, s[6:7]
	v_or_b32_e32 v56, s28, v161
	global_load_dwordx4 v[148:151], v[58:59], off offset:2112
	v_lshl_or_b32 v57, v56, 8, v170
	global_load_dwordx4 v[152:155], v[52:53], off offset:16
	s_waitcnt vmcnt(0)
	v_cvt_pk_bf16_f32 v112, v60, v61
	v_cvt_pk_bf16_f32 v113, v62, v63
	v_cvt_pk_bf16_f32 v114, v64, v65
	v_cvt_pk_bf16_f32 v115, v66, v67
	v_cvt_pk_bf16_f32 v116, v68, v69
	v_cvt_pk_bf16_f32 v117, v70, v71
	v_cvt_pk_bf16_f32 v118, v72, v73
	v_cvt_pk_bf16_f32 v119, v74, v75
	v_cvt_pk_bf16_f32 v120, v76, v77
	v_cvt_pk_bf16_f32 v121, v78, v79
	v_cvt_pk_bf16_f32 v122, v80, v81
	v_cvt_pk_bf16_f32 v123, v82, v83
	v_cvt_pk_bf16_f32 v124, v84, v85
	v_cvt_pk_bf16_f32 v125, v86, v87
	v_cvt_pk_bf16_f32 v126, v88, v89
	v_cvt_pk_bf16_f32 v127, v90, v91
	v_cvt_pk_bf16_f32 v128, v92, v93
	v_cvt_pk_bf16_f32 v129, v94, v95
	v_cvt_pk_bf16_f32 v130, v96, v97
	v_cvt_pk_bf16_f32 v131, v98, v99
	v_cvt_pk_bf16_f32 v132, v100, v101
	v_cvt_pk_bf16_f32 v133, v102, v103
	v_cvt_pk_bf16_f32 v134, v104, v105
	v_cvt_pk_bf16_f32 v135, v106, v107
	v_cvt_pk_bf16_f32 v136, v108, v109
	v_cvt_pk_bf16_f32 v137, v110, v111
	v_cvt_pk_bf16_f32 v138, v140, v141
	v_cvt_pk_bf16_f32 v139, v142, v143
	v_cvt_pk_bf16_f32 v144, v148, v149
	v_cvt_pk_bf16_f32 v145, v150, v151
	v_cvt_pk_bf16_f32 v146, v152, v153
	v_cvt_pk_bf16_f32 v147, v154, v155
	global_load_dwordx4 v[96:99], v57, s[58:59]
	global_load_dwordx4 v[100:103], v57, s[56:57]
	s_load_dwordx2 s[6:7], s[0:1], 0xa8
	v_lshlrev_b32_e32 v56, 2, v56
	v_mov_b64_e32 v[60:61], v[124:125]
	v_mov_b64_e32 v[64:65], v[128:129]
	v_mov_b64_e32 v[68:69], v[132:133]
	s_waitcnt lgkmcnt(0)
	global_load_dword v204, v56, s[6:7]
	v_mov_b64_e32 v[72:73], v[136:137]
	v_mov_b64_e32 v[76:77], v[144:145]
	v_mov_b64_e32 v[62:63], v[126:127]
	v_mov_b64_e32 v[66:67], v[130:131]
	v_mov_b64_e32 v[70:71], v[134:135]
	v_mov_b64_e32 v[74:75], v[138:139]
	v_mov_b64_e32 v[78:79], v[146:147]
	global_load_dwordx4 v[104:107], v57, s[58:59] offset:64
	global_load_dwordx4 v[108:111], v57, s[56:57] offset:64
	global_load_dwordx4 v[206:209], v57, s[58:59] offset:128
	global_load_dwordx4 v[210:213], v57, s[56:57] offset:128
	global_load_dwordx4 v[214:217], v57, s[58:59] offset:192
	global_load_dwordx4 v[218:221], v57, s[56:57] offset:192
	v_mov_b64_e32 v[52:53], v[116:117]
	v_mov_b64_e32 v[56:57], v[120:121]
	v_mov_b64_e32 v[54:55], v[118:119]
	v_mov_b64_e32 v[58:59], v[122:123]
	s_waitcnt vmcnt(0)
	v_xor_b32_e32 v48, 0x80000000, v96
	v_xor_b32_e32 v49, 0x80000000, v97
	v_xor_b32_e32 v50, 0x80000000, v98
	v_xor_b32_e32 v51, 0x80000000, v99
	v_cvt_pk_bf16_f32 v140, v100, v48
	v_cvt_pk_bf16_f32 v141, v101, v49
	v_cvt_pk_bf16_f32 v142, v102, v50
	v_cvt_pk_bf16_f32 v143, v103, v51
	v_xor_b32_e32 v48, 0x80000000, v104
	v_xor_b32_e32 v49, 0x80000000, v105
	v_xor_b32_e32 v50, 0x80000000, v106
	v_xor_b32_e32 v51, 0x80000000, v107
	v_cvt_pk_bf16_f32 v148, v108, v48
	v_cvt_pk_bf16_f32 v149, v109, v49
	v_cvt_pk_bf16_f32 v150, v110, v50
	v_cvt_pk_bf16_f32 v151, v111, v51
	v_mov_b64_e32 v[80:81], v[148:149]
	v_mov_b64_e32 v[82:83], v[150:151]
	v_xor_b32_e32 v48, 0x80000000, v206
	v_xor_b32_e32 v49, 0x80000000, v207
	v_xor_b32_e32 v50, 0x80000000, v208
	v_xor_b32_e32 v51, 0x80000000, v209
	v_cvt_pk_bf16_f32 v152, v210, v48
	v_cvt_pk_bf16_f32 v153, v211, v49
	v_cvt_pk_bf16_f32 v154, v212, v50
	v_cvt_pk_bf16_f32 v155, v213, v51
	v_mov_b64_e32 v[48:49], v[112:113]
	v_mov_b64_e32 v[84:85], v[152:153]
	v_mov_b64_e32 v[50:51], v[114:115]
	v_mov_b64_e32 v[86:87], v[154:155]
	v_xor_b32_e32 v88, 0x80000000, v214
	v_xor_b32_e32 v89, 0x80000000, v215
	v_xor_b32_e32 v90, 0x80000000, v216
	v_xor_b32_e32 v91, 0x80000000, v217
	v_cvt_pk_bf16_f32 v156, v218, v88
	v_cvt_pk_bf16_f32 v157, v219, v89
	v_cvt_pk_bf16_f32 v158, v220, v90
	v_cvt_pk_bf16_f32 v159, v221, v91
	v_mov_b64_e32 v[92:93], v[140:141]
	v_mov_b64_e32 v[88:89], v[156:157]
	v_mov_b64_e32 v[90:91], v[158:159]
	v_mov_b64_e32 v[94:95], v[142:143]
